# attention unmasked loop: exp(p1) consumers (cvt, row sums) deferred to the next iteration head under the K-fragment LDS latency and QK MFMA gaps
# baseline (speedup 1.0000x reference)
.Lattn_u_entry:
	s_setprio 1
	s_bitcmp1_b32 s4, 0
	s_cselect_b32 s30, 0x4400, 0
	v_add_u32_e32 v0, s30, v224
	s_mul_i32 s30, s6, 0x5000
	ds_read_b128 v[2:5], v0
	ds_read_b128 v[6:9], v0 offset:8704
	v_add_u32_e32 v21, s30, v225
	ds_read_b128 v[10:13], v0 offset:32
	ds_read_b128 v[28:31], v0 offset:8736
	ds_read_b128 v[236:239], v0 offset:64
	ds_read_b128 v[240:243], v0 offset:8768
	ds_read_b128 v[24:27], v0 offset:96
	s_waitcnt lgkmcnt(6)
	v_mfma_f32_32x32x16_bf16 v[128:143], v[2:5], v[144:147], v[96:111]
	ds_read_b128 v[2:5], v0 offset:8800
	s_waitcnt lgkmcnt(6)
	v_mfma_f32_32x32x16_bf16 v[112:127], v[6:9], v[144:147], v[96:111]
	ds_read_b64_tr_b16 v[6:7], v21 offset:34816
	ds_read_b64_tr_b16 v[8:9], v21 offset:37376
	s_branch .Lattn_u_body
.LBB0_581:
	s_setprio 1
	s_bitcmp1_b32 s4, 0
	s_cselect_b32 s30, 0x4400, 0
	v_add_u32_e32 v0, s30, v224
	s_mul_i32 s30, s6, 0x5000
	ds_read_b128 v[2:5], v0
	ds_read_b128 v[6:9], v0 offset:8704
	v_add_u32_e32 v21, s30, v225
	ds_read_b128 v[10:13], v0 offset:32
	ds_read_b128 v[28:31], v0 offset:8736
	ds_read_b128 v[236:239], v0 offset:64
	ds_read_b128 v[240:243], v0 offset:8768
	ds_read_b128 v[24:27], v0 offset:96
	v_cvt_pk_bf16_f32 v180, v112, v113
	v_cvt_pk_bf16_f32 v181, v114, v115
	v_cvt_pk_bf16_f32 v182, v116, v117
	v_cvt_pk_bf16_f32 v183, v118, v119
	v_cvt_pk_bf16_f32 v176, v120, v121
	v_cvt_pk_bf16_f32 v177, v122, v123
	v_cvt_pk_bf16_f32 v178, v124, v125
	v_cvt_pk_bf16_f32 v179, v126, v127
	v_add_f32_e32 v19, v112, v113
	v_add_f32_e32 v20, v120, v121
	v_add_f32_e32 v19, v19, v114
	v_add_f32_e32 v20, v20, v122
	v_add_f32_e32 v19, v19, v115
	v_add_f32_e32 v20, v20, v123
	v_add_f32_e32 v19, v19, v116
	v_add_f32_e32 v20, v20, v124
	s_waitcnt lgkmcnt(6)
	v_mfma_f32_32x32x16_bf16 v[128:143], v[2:5], v[144:147], v[96:111]
	ds_read_b128 v[2:5], v0 offset:8800
	v_add_f32_e32 v19, v19, v117
	v_add_f32_e32 v20, v20, v125
	v_add_f32_e32 v19, v19, v118
	v_add_f32_e32 v20, v20, v126
	v_add_f32_e32 v19, v19, v119
	v_add_f32_e32 v20, v20, v127
	v_add_f32_e32 v19, v19, v20
	v_add_f32_e32 v17, v17, v19
	v_add_f32_e32 v211, v211, v17
	s_waitcnt lgkmcnt(6)
	v_mfma_f32_32x32x16_bf16 v[112:127], v[6:9], v[144:147], v[96:111]
	ds_read_b64_tr_b16 v[6:7], v21 offset:34816
	ds_read_b64_tr_b16 v[8:9], v21 offset:37376
.Lattn_u_body:
	s_waitcnt lgkmcnt(7)
	v_mfma_f32_32x32x16_bf16 v[128:143], v[10:13], v[148:151], v[128:143]
	ds_read_b64_tr_b16 v[10:11], v21 offset:34880
	ds_read_b64_tr_b16 v[12:13], v21 offset:37440
	s_waitcnt lgkmcnt(8)
	v_mfma_f32_32x32x16_bf16 v[112:127], v[28:31], v[148:151], v[112:127]
	ds_read_b64_tr_b16 v[28:29], v21 offset:34944
	ds_read_b64_tr_b16 v[30:31], v21 offset:37504
	s_waitcnt lgkmcnt(9)
	v_mfma_f32_32x32x16_bf16 v[128:143], v[236:239], v[152:155], v[128:143]
	ds_read_b64_tr_b16 v[236:237], v21 offset:35008
	ds_read_b64_tr_b16 v[238:239], v21 offset:37568
	s_waitcnt lgkmcnt(10)
	v_mfma_f32_32x32x16_bf16 v[112:127], v[240:243], v[152:155], v[112:127]
	ds_read_b64_tr_b16 v[240:241], v21 offset:39936
	ds_read_b64_tr_b16 v[242:243], v21 offset:42496
	s_waitcnt lgkmcnt(11)
	v_mfma_f32_32x32x16_bf16 v[128:143], v[24:27], v[156:159], v[128:143]
	ds_read_b64_tr_b16 v[24:25], v21 offset:40000
	ds_read_b64_tr_b16 v[26:27], v21 offset:42560
	s_waitcnt lgkmcnt(12)
	v_mfma_f32_32x32x16_bf16 v[112:127], v[2:5], v[156:159], v[112:127]
	ds_read_b64_tr_b16 v[2:3], v21 offset:40064
	ds_read_b64_tr_b16 v[4:5], v21 offset:42624
	s_waitcnt lgkmcnt(12)
	v_mfma_f32_32x32x16_bf16 v[64:79], v[188:191], v[6:9], v[64:79]
	ds_read_b64_tr_b16 v[6:7], v21 offset:40128
	ds_read_b64_tr_b16 v[8:9], v21 offset:42688
	s_nop 1
	v_exp_f32_e32 v128, v128
	v_exp_f32_e32 v129, v129
	v_exp_f32_e32 v130, v130
	s_waitcnt lgkmcnt(12)
	v_mfma_f32_32x32x16_bf16 v[80:95], v[188:191], v[10:13], v[80:95]
	ds_read_b64_tr_b16 v[10:11], v21 offset:45056
	ds_read_b64_tr_b16 v[12:13], v21 offset:47616
	v_exp_f32_e32 v131, v131
	v_exp_f32_e32 v132, v132
	v_exp_f32_e32 v133, v133
	s_waitcnt lgkmcnt(12)
	v_mfma_f32_32x32x16_bf16 v[48:63], v[188:191], v[28:31], v[48:63]
	ds_read_b64_tr_b16 v[28:29], v21 offset:45120
	ds_read_b64_tr_b16 v[30:31], v21 offset:47680
	v_exp_f32_e32 v134, v134
	v_exp_f32_e32 v135, v135
	v_exp_f32_e32 v136, v136
	s_waitcnt lgkmcnt(12)
	v_mfma_f32_32x32x16_bf16 v[32:47], v[188:191], v[236:239], v[32:47]
	ds_read_b64_tr_b16 v[236:237], v21 offset:45184
	ds_read_b64_tr_b16 v[238:239], v21 offset:47744
	v_exp_f32_e32 v137, v137
	v_exp_f32_e32 v138, v138
	v_exp_f32_e32 v139, v139
	s_waitcnt lgkmcnt(12)
	v_mfma_f32_32x32x16_bf16 v[64:79], v[184:187], v[240:243], v[64:79]
	ds_read_b64_tr_b16 v[240:241], v21 offset:45248
	ds_read_b64_tr_b16 v[242:243], v21 offset:47808
	v_exp_f32_e32 v140, v140
	v_exp_f32_e32 v141, v141
	v_exp_f32_e32 v142, v142
	s_waitcnt lgkmcnt(12)
	v_mfma_f32_32x32x16_bf16 v[80:95], v[184:187], v[24:27], v[80:95]
	ds_read_b64_tr_b16 v[24:25], v21 offset:50176
	ds_read_b64_tr_b16 v[26:27], v21 offset:52736
	v_exp_f32_e32 v143, v143
	v_exp_f32_e32 v112, v112
	v_exp_f32_e32 v113, v113
	s_waitcnt lgkmcnt(12)
	v_mfma_f32_32x32x16_bf16 v[48:63], v[184:187], v[2:5], v[48:63]
	ds_read_b64_tr_b16 v[2:3], v21 offset:50240
	ds_read_b64_tr_b16 v[4:5], v21 offset:52800
	v_exp_f32_e32 v114, v114
	v_exp_f32_e32 v115, v115
	v_exp_f32_e32 v116, v116
	s_waitcnt lgkmcnt(12)
	v_mfma_f32_32x32x16_bf16 v[32:47], v[184:187], v[6:9], v[32:47]
	ds_read_b64_tr_b16 v[6:7], v21 offset:50304
	ds_read_b64_tr_b16 v[8:9], v21 offset:52864
	s_andn2_b32 s30, 1, s4
	s_mulk_i32 s30, 0x4400
	s_mul_i32 s31, s34, 0x5000
	v_add3_u32 v22, v223, s30, v228
	v_add3_u32 v23, v223, s31, v229
	v_exp_f32_e32 v117, v117
	v_exp_f32_e32 v118, v118
	v_exp_f32_e32 v119, v119
	s_waitcnt lgkmcnt(12)
	v_mfma_f32_32x32x16_bf16 v[64:79], v[180:183], v[10:13], v[64:79]
	ds_read_b64_tr_b16 v[10:11], v21 offset:50368
	ds_read_b64_tr_b16 v[12:13], v21 offset:52928
	s_waitcnt vmcnt(3)
	ds_write_b128 v22, v[160:163]
	v_exp_f32_e32 v120, v120
	v_exp_f32_e32 v121, v121
	v_exp_f32_e32 v122, v122
	s_waitcnt lgkmcnt(13)
	v_mfma_f32_32x32x16_bf16 v[80:95], v[180:183], v[28:31], v[80:95]
	s_waitcnt vmcnt(2)
	ds_write_b128 v23, v[164:167] offset:34816
	v_exp_f32_e32 v123, v123
	v_exp_f32_e32 v124, v124
	v_exp_f32_e32 v125, v125
	s_waitcnt lgkmcnt(12)
	v_mfma_f32_32x32x16_bf16 v[48:63], v[180:183], v[236:239], v[48:63]
	s_waitcnt vmcnt(1)
	ds_write_b128 v22, v[168:171] offset:8704
	v_exp_f32_e32 v126, v126
	v_exp_f32_e32 v127, v127
	v_cvt_pk_bf16_f32 v188, v128, v129
	v_cvt_pk_bf16_f32 v189, v130, v131
	s_waitcnt lgkmcnt(11)
	v_mfma_f32_32x32x16_bf16 v[32:47], v[180:183], v[240:243], v[32:47]
	s_waitcnt vmcnt(0)
	ds_write_b128 v23, v[172:175] offset:45056
	v_cvt_pk_bf16_f32 v190, v132, v133
	v_cvt_pk_bf16_f32 v191, v134, v135
	v_cvt_pk_bf16_f32 v184, v136, v137
	v_cvt_pk_bf16_f32 v185, v138, v139
	v_cvt_pk_bf16_f32 v186, v140, v141
	v_cvt_pk_bf16_f32 v187, v142, v143
	s_waitcnt lgkmcnt(10)
	v_mfma_f32_32x32x16_bf16 v[64:79], v[176:179], v[24:27], v[64:79]
	v_add_f32_e32 v17, v128, v129
	v_add_f32_e32 v17, v17, v130
	v_add_f32_e32 v17, v17, v131
	v_add_f32_e32 v17, v17, v132
	v_add_f32_e32 v17, v17, v133
	v_add_f32_e32 v17, v17, v134
	s_waitcnt lgkmcnt(8)
	v_mfma_f32_32x32x16_bf16 v[80:95], v[176:179], v[2:5], v[80:95]
	v_add_f32_e32 v17, v17, v135
	v_add_f32_e32 v18, v136, v137
	v_add_f32_e32 v18, v18, v138
	v_add_f32_e32 v18, v18, v139
	v_add_f32_e32 v18, v18, v140
	v_add_f32_e32 v18, v18, v141
	s_add_i32 s30, s4, 2
	s_cmp_ge_i32 s30, s27
	s_cbranch_scc1 .Lattn_u_skipld
	s_sub_i32 s30, s5, 32
	v_mad_u64_u32 v[22:23], s[30:31], s30, v219, v[202:203]
	global_load_dwordx4 v[160:163], v[22:23], off
	global_load_dwordx4 v[164:167], v[22:23], off offset:1024
	v_mad_u64_u32 v[22:23], s[30:31], s5, v219, v[202:203]
	global_load_dwordx4 v[168:171], v[22:23], off
	global_load_dwordx4 v[172:175], v[22:23], off offset:1024
.Lattn_u_skipld:
	s_waitcnt lgkmcnt(6)
	v_mfma_f32_32x32x16_bf16 v[48:63], v[176:179], v[6:9], v[48:63]
	v_add_f32_e32 v18, v18, v142
	v_add_f32_e32 v18, v18, v143
	v_add_f32_e32 v17, v17, v18
	s_waitcnt lgkmcnt(4)
	v_mfma_f32_32x32x16_bf16 v[32:47], v[176:179], v[10:13], v[32:47]
	s_setprio 0
	s_add_i32 s30, s6, 1
	s_cmp_lg_u32 s6, 2
	s_cselect_b32 s6, s30, 0
	s_add_i32 s30, s34, 1
	s_cmp_lg_u32 s34, 2
	s_cselect_b32 s34, s30, 0
	s_add_i32 s4, s4, 1
	s_add_i32 s5, s5, 64
	s_cmp_eq_u32 s35, s4
	s_waitcnt lgkmcnt(0)
	s_barrier
	s_cbranch_scc0 .LBB0_581
	v_cvt_pk_bf16_f32 v180, v112, v113
	v_cvt_pk_bf16_f32 v181, v114, v115
	v_cvt_pk_bf16_f32 v182, v116, v117
	v_cvt_pk_bf16_f32 v183, v118, v119
	v_cvt_pk_bf16_f32 v176, v120, v121
	v_cvt_pk_bf16_f32 v177, v122, v123
	v_cvt_pk_bf16_f32 v178, v124, v125
	v_cvt_pk_bf16_f32 v179, v126, v127
	v_add_f32_e32 v19, v112, v113
	v_add_f32_e32 v20, v120, v121
	v_add_f32_e32 v19, v19, v114
	v_add_f32_e32 v20, v20, v122
	v_add_f32_e32 v19, v19, v115
	v_add_f32_e32 v20, v20, v123
	v_add_f32_e32 v19, v19, v116
	v_add_f32_e32 v20, v20, v124
	v_add_f32_e32 v19, v19, v117
	v_add_f32_e32 v20, v20, v125
	v_add_f32_e32 v19, v19, v118
	v_add_f32_e32 v20, v20, v126
	v_add_f32_e32 v19, v19, v119
	v_add_f32_e32 v20, v20, v127
	v_add_f32_e32 v19, v19, v20
	v_add_f32_e32 v17, v17, v19
	v_add_f32_e32 v211, v211, v17
	s_branch .LBB0_584
